# v36_prio_mirror
# speedup vs baseline: 1.0059x; 1.0059x over previous
; #define PG8_STAGE(bufoff, gbase, voff) do { const __amdgpu_buffer_rsrc_t _rs = __builtin_amdgcn_make_buffer_rsrc((void*)(gbase), 0, 0x7fffffff, 0x00020000); _Pragma("unroll") for (int _i = 0; _i < 2; ++_i) \
;         __builtin_amdgcn_raw_ptr_buffer_load_lds(_rs, (LAS unsigned*)(lds + (bufoff) + ldsw + _i * 8192), 16, (int)(voff)[_i], 0, 0, 0); } while (0)
; #define PG8_BAR __builtin_amdgcn_s_barrier()
; template <class Epi, class Sched, bool F8 = false>
; __device__ __forceinline__ void gemm_phase(LAS unsigned char* lds, const int lda, const int ldb, const Sched& S, const Epi& E) {
;     ...
;     const int tid = tid_, wid = __builtin_amdgcn_readfirstlane(tid >> 6), lane = tid & 63, wr = wid >> 2, wc = wid & 3, fr = lane & 15, fq = lane >> 4;
;     unsigned voffA[2], voffB[2];
; #pragma unroll
;     for (int i = 0; i < 2; ++i) { int R, C; stage_rc(tid * 16 + i * 8192, R, C); const int Rb = Epi::PERM ? ((R & ~31) + perm32(R & 31)) : R;
;         voffA[i] = (unsigned)(R * lda + C * 2); voffB[i] = (unsigned)(Rb * 128 + C * 2); }
;     const size_t kstep = (size_t)(BK * 2), kstepB = 32768;
;     const size_t hstepA = (size_t)HALF * lda, hstepB = 16384; (void)ldb;
;     const unsigned ldsw = (unsigned)wid * 1024u;
;     const int aoff = lds_byte(wr * 64 + fr, fq * 8), boff = lds_byte(wc * 32 + fr, fq * 8);
;     ...
;     Unit cur, nxt; int ui = 0;
;     if (!S.next(0, cur)) return;
;     f32x4 acc[2][2][4][2];
; #pragma unroll
;     for (int a = 0; a < 2; ++a)
; #pragma unroll
;         for (int b = 0; b < 2; ++b)
; #pragma unroll
;             for (int m = 0; m < 4; ++m)
; #pragma unroll
;                 for (int n = 0; n < 2; ++n) acc[a][b][m][n] = (f32x4){0.f, 0.f, 0.f, 0.f};
;     bf16x8 At[4][2], B0[2][2], B1[2][2]; i32x8 At8[4], B08[2], B18[2];
;     const char* cA = cur.A; const char* cB = cur.B;
;     ...
;     PG8_STAGE(PG8_SB(0, 0), cB, voffB); PG8_STAGE(PG8_SB(0, 1), cB + hstepB, voffB); PG8_STAGE(PG8_SA(0, 0), cA, voffA); PG8_STAGE(PG8_SA(0, 1), cA + hstepA, voffA);
;     if (wr == 1) PG8_BAR;
.LBB0_104:
	v_bfe_i32 v3, v0, 27, 1
	v_lshlrev_b32_e32 v1, 4, v0
	v_lshrrev_b32_e32 v3, 22, v3
	v_add_u32_e32 v3, v1, v3
	v_and_b32_e32 v3, 0xfffffc00, v3
	v_sub_u32_e32 v3, v1, v3
	v_ashrrev_i32_e32 v2, 31, v0
	v_lshrrev_b32_e32 v4, 4, v3
	v_lshrrev_b32_e32 v2, 26, v2
	v_bitop3_b32 v3, v4, v3, 32 bitop3:0x6c
	v_add_u32_e32 v2, v0, v2
	v_ashrrev_i32_e32 v5, 31, v3
	v_ashrrev_i32_e32 v2, 6, v2
	v_lshrrev_b32_e32 v5, 26, v5
	v_lshlrev_b32_e32 v4, 3, v2
	v_add_u32_e32 v5, v3, v5
	v_and_b32_e32 v4, -16, v4
	v_ashrrev_i32_e32 v6, 6, v5
	v_and_b32_e32 v5, 0xc0, v5
	v_add_u32_e32 v4, v6, v4
	v_sub_u32_e32 v3, v3, v5
	v_mov_b32_e32 v5, 1
	v_lshlrev_b32_e32 v2, 5, v2
	v_ashrrev_i16_sdwa v3, v5, sext(v3) dst_sel:DWORD dst_unused:UNUSED_PAD src0_sel:DWORD src1_sel:BYTE_0
	v_lshlrev_b32_e32 v7, 1, v4
	v_lshrrev_b32_e32 v8, 2, v4
	v_and_b32_e32 v6, 3, v6
	s_mov_b32 s3, 0x1ffffe0
	v_and_b32_e32 v2, 32, v2
	v_bfe_i32 v3, v3, 0, 16
	v_and_b32_e32 v7, 24, v7
	v_and_b32_e32 v8, 4, v8
	v_and_or_b32 v6, v4, s3, v6
	v_or3_b32 v6, v6, v8, v7
	v_add_lshl_u32 v2, v2, v3, 1
	v_add_u32_e32 v1, 0x2000, v1
	v_lshl_add_u32 v136, v4, 13, v2
	v_lshl_add_u32 v137, v6, 7, v2
	v_ashrrev_i32_e32 v2, 31, v1
	v_lshrrev_b32_e32 v2, 22, v2
	v_add_u32_e32 v2, v1, v2
	v_ashrrev_i32_e32 v2, 10, v2
	v_mul_i32_i24_e32 v3, 0x400, v2
	v_sub_u32_e32 v1, v1, v3
	v_lshrrev_b32_e32 v3, 4, v1
	v_bitop3_b32 v1, v3, v1, 32 bitop3:0x6c
	v_ashrrev_i32_e32 v4, 31, v1
	v_lshrrev_b32_e32 v4, 26, v4
	v_lshlrev_b32_e32 v3, 3, v2
	v_add_u32_e32 v4, v1, v4
	v_and_b32_e32 v3, -16, v3
	v_ashrrev_i32_e32 v6, 6, v4
	v_add_u32_e32 v3, v6, v3
	v_and_b32_e32 v4, 0xc0, v4
	v_and_b32_e32 v6, 3, v6
	s_ashr_i32 s5, s24, 6
	v_sub_u32_e32 v1, v1, v4
	v_and_or_b32 v6, v3, s3, v6
	s_lshl_b32 s3, s5, 10
	v_lshlrev_b32_e32 v2, 5, v2
	v_ashrrev_i16_sdwa v1, v5, sext(v1) dst_sel:DWORD dst_unused:UNUSED_PAD src0_sel:DWORD src1_sel:BYTE_0
	v_lshlrev_b32_e32 v4, 1, v3
	v_lshrrev_b32_e32 v5, 2, v3
	s_add_i32 s3, s3, 0
	v_and_b32_e32 v2, 32, v2
	v_bfe_i32 v1, v1, 0, 16
	v_and_b32_e32 v4, 24, v4
	v_and_b32_e32 v5, 4, v5
	s_add_i32 s8, s3, 0x10000
	v_or3_b32 v4, v6, v5, v4
	v_add_lshl_u32 v1, v2, v1, 1
	s_and_b32 s17, s23, 0xffff
	s_mov_b32 s19, 0x20000
	s_brev_b32 s18, -2
	s_mov_b32 s16, s22
	s_mov_b32 m0, s8
	s_add_i32 s9, s3, 0x12000
	s_ashr_i32 s4, s24, 8
	v_lshl_add_u32 v139, v4, 7, v1
	buffer_load_dwordx4 v137, s[16:19], 0 offen lds
	s_mov_b32 m0, s9
	v_lshl_add_u32 v138, v3, 13, v1
	buffer_load_dwordx4 v139, s[16:19], 0 offen lds
	s_add_u32 s16, s22, 0x4000
	s_addc_u32 s7, s23, 0
	s_add_i32 s76, s3, 0x14000
	s_and_b32 s17, s7, 0xffff
	s_mov_b32 m0, s76
	s_add_i32 s79, s3, 0x16000
	buffer_load_dwordx4 v137, s[16:19], 0 offen lds
	s_mov_b32 m0, s79
	s_add_i32 s80, s3, 0x2000
	buffer_load_dwordx4 v139, s[16:19], 0 offen lds
	s_and_b32 s17, s21, 0xffff
	s_mov_b32 s16, s20
	s_mov_b32 m0, s3
	s_mov_b32 s83, 0
	buffer_load_dwordx4 v136, s[16:19], 0 offen lds
	s_mov_b32 m0, s80
	s_movk_i32 s84, 0x6000
	buffer_load_dwordx4 v138, s[16:19], 0 offen lds
	s_add_u32 s16, s20, 0x100000
	s_addc_u32 s7, s21, 0
	s_add_i32 s81, s3, 0x4000
	s_and_b32 s17, s7, 0xffff
	s_mov_b32 m0, s81
	s_add_i32 s82, s3, 0x6000
	buffer_load_dwordx4 v136, s[16:19], 0 offen lds
	s_mov_b32 m0, s82
	s_cmp_eq_u32 s4, 1
	buffer_load_dwordx4 v138, s[16:19], 0 offen lds
	s_cselect_b64 s[36:37], -1, 0
	s_cmp_lg_u32 s4, 1
	s_setprio 1
	s_cbranch_scc1 .LBB0_106
	s_setprio 0
	s_barrier

; #define PG8_STAGE(bufoff, gbase, voff) do { const __amdgpu_buffer_rsrc_t _rs = __builtin_amdgcn_make_buffer_rsrc((void*)(gbase), 0, 0x7fffffff, 0x00020000); _Pragma("unroll") for (int _i = 0; _i < 2; ++_i) \
;         __builtin_amdgcn_raw_ptr_buffer_load_lds(_rs, (LAS unsigned*)(lds + (bufoff) + ldsw + _i * 8192), 16, (int)(voff)[_i], 0, 0, 0); } while (0)
; #define PG8_BAR __builtin_amdgcn_s_barrier()
; template <class Epi, class Sched, bool F8 = false>
; __device__ __forceinline__ void gemm_phase(LAS unsigned char* lds, const int lda, const int ldb, const Sched& S, const Epi& E) {
;     ...
;     const int tid = tid_, wid = __builtin_amdgcn_readfirstlane(tid >> 6), lane = tid & 63, wr = wid >> 2, wc = wid & 3, fr = lane & 15, fq = lane >> 4;
;     unsigned voffA[2], voffB[2];
; #pragma unroll
;     for (int i = 0; i < 2; ++i) { int R, C; stage_rc(tid * 16 + i * 8192, R, C); const int Rb = Epi::PERM ? ((R & ~31) + perm32(R & 31)) : R;
;         voffA[i] = (unsigned)(R * lda + C * 2); voffB[i] = (unsigned)(Rb * 128 + C * 2); }
;     const size_t kstep = (size_t)(BK * 2), kstepB = 32768;
;     const size_t hstepA = (size_t)HALF * lda, hstepB = 16384; (void)ldb;
;     const unsigned ldsw = (unsigned)wid * 1024u;
;     const int aoff = lds_byte(wr * 64 + fr, fq * 8), boff = lds_byte(wc * 32 + fr, fq * 8);
;     ...
;     Unit cur, nxt; int ui = 0;
;     if (!S.next(0, cur)) return;
;     f32x4 acc[2][2][4][2];
; #pragma unroll
;     for (int a = 0; a < 2; ++a)
; #pragma unroll
;         for (int b = 0; b < 2; ++b)
; #pragma unroll
;             for (int m = 0; m < 4; ++m)
; #pragma unroll
;                 for (int n = 0; n < 2; ++n) acc[a][b][m][n] = (f32x4){0.f, 0.f, 0.f, 0.f};
;     bf16x8 At[4][2], B0[2][2], B1[2][2]; i32x8 At8[4], B08[2], B18[2];
;     const char* cA = cur.A; const char* cB = cur.B;
;     ...
;     PG8_STAGE(PG8_SB(0, 0), cB, voffB); PG8_STAGE(PG8_SB(0, 1), cB + hstepB, voffB); PG8_STAGE(PG8_SA(0, 0), cA, voffA); PG8_STAGE(PG8_SA(0, 1), cA + hstepA, voffA);
;     if (wr == 1) PG8_BAR;
.LBB0_162:
	v_bfe_i32 v3, v0, 27, 1
	v_lshlrev_b32_e32 v1, 4, v0
	v_lshrrev_b32_e32 v3, 22, v3
	v_add_u32_e32 v3, v1, v3
	v_and_b32_e32 v3, 0xfffffc00, v3
	v_sub_u32_e32 v3, v1, v3
	v_ashrrev_i32_e32 v2, 31, v0
	v_lshrrev_b32_e32 v4, 4, v3
	v_lshrrev_b32_e32 v2, 26, v2
	v_bitop3_b32 v3, v4, v3, 32 bitop3:0x6c
	v_add_u32_e32 v2, v0, v2
	v_ashrrev_i32_e32 v5, 31, v3
	v_ashrrev_i32_e32 v2, 6, v2
	v_lshrrev_b32_e32 v5, 26, v5
	v_lshlrev_b32_e32 v4, 3, v2
	v_add_u32_e32 v5, v3, v5
	v_and_b32_e32 v4, -16, v4
	v_ashrrev_i32_e32 v6, 6, v5
	v_and_b32_e32 v5, 0xc0, v5
	v_add_u32_e32 v4, v6, v4
	v_sub_u32_e32 v3, v3, v5
	v_mov_b32_e32 v5, 1
	v_lshlrev_b32_e32 v2, 5, v2
	v_ashrrev_i16_sdwa v3, v5, sext(v3) dst_sel:DWORD dst_unused:UNUSED_PAD src0_sel:DWORD src1_sel:BYTE_0
	v_lshlrev_b32_e32 v7, 1, v4
	v_lshrrev_b32_e32 v8, 2, v4
	v_and_b32_e32 v6, 3, v6
	s_mov_b32 s5, 0x1ffffe0
	v_and_b32_e32 v2, 32, v2
	v_bfe_i32 v3, v3, 0, 16
	v_and_b32_e32 v7, 24, v7
	v_and_b32_e32 v8, 4, v8
	v_and_or_b32 v6, v4, s5, v6
	v_or3_b32 v6, v6, v8, v7
	v_add_lshl_u32 v2, v2, v3, 1
	v_add_u32_e32 v1, 0x2000, v1
	v_lshl_add_u32 v136, v4, 12, v2
	v_lshl_add_u32 v137, v6, 7, v2
	v_ashrrev_i32_e32 v2, 31, v1
	v_lshrrev_b32_e32 v2, 22, v2
	v_add_u32_e32 v2, v1, v2
	v_ashrrev_i32_e32 v2, 10, v2
	v_mul_i32_i24_e32 v3, 0x400, v2
	v_sub_u32_e32 v1, v1, v3
	v_lshrrev_b32_e32 v3, 4, v1
	v_bitop3_b32 v1, v3, v1, 32 bitop3:0x6c
	v_ashrrev_i32_e32 v4, 31, v1
	v_lshrrev_b32_e32 v4, 26, v4
	v_lshlrev_b32_e32 v3, 3, v2
	v_add_u32_e32 v4, v1, v4
	v_and_b32_e32 v3, -16, v3
	v_ashrrev_i32_e32 v6, 6, v4
	v_add_u32_e32 v3, v6, v3
	v_and_b32_e32 v6, 3, v6
	v_and_b32_e32 v4, 0xc0, v4
	v_and_or_b32 v6, v3, s5, v6
	s_ashr_i32 s5, s3, 6
	v_sub_u32_e32 v1, v1, v4
	s_lshl_b32 s7, s5, 10
	v_lshlrev_b32_e32 v2, 5, v2
	v_ashrrev_i16_sdwa v1, v5, sext(v1) dst_sel:DWORD dst_unused:UNUSED_PAD src0_sel:DWORD src1_sel:BYTE_0
	v_lshlrev_b32_e32 v4, 1, v3
	v_lshrrev_b32_e32 v5, 2, v3
	s_add_i32 s76, s7, 0
	v_and_b32_e32 v2, 32, v2
	v_bfe_i32 v1, v1, 0, 16
	v_and_b32_e32 v4, 24, v4
	v_and_b32_e32 v5, 4, v5
	s_add_i32 s79, s76, 0x10000
	v_or3_b32 v4, v6, v5, v4
	v_add_lshl_u32 v1, v2, v1, 1
	s_and_b32 s17, s23, 0xffff
	s_mov_b32 s19, 0x20000
	s_brev_b32 s18, -2
	s_mov_b32 s16, s22
	s_mov_b32 m0, s79
	s_add_i32 s80, s76, 0x12000
	s_ashr_i32 s4, s3, 8
	v_lshl_add_u32 v139, v4, 7, v1
	buffer_load_dwordx4 v137, s[16:19], 0 offen lds
	s_mov_b32 m0, s80
	v_lshl_add_u32 v138, v3, 12, v1
	buffer_load_dwordx4 v139, s[16:19], 0 offen lds
	s_add_u32 s16, s22, 0x4000
	s_addc_u32 s7, s23, 0
	s_add_i32 s81, s76, 0x14000
	s_and_b32 s17, s7, 0xffff
	s_mov_b32 m0, s81
	s_add_i32 s82, s76, 0x16000
	buffer_load_dwordx4 v137, s[16:19], 0 offen lds
	s_mov_b32 m0, s82
	s_add_i32 s83, s76, 0x2000
	buffer_load_dwordx4 v139, s[16:19], 0 offen lds
	s_and_b32 s17, s21, 0xffff
	s_mov_b32 s16, s20
	s_mov_b32 m0, s76
	s_mov_b32 s86, 0
	buffer_load_dwordx4 v136, s[16:19], 0 offen lds
	s_mov_b32 m0, s83
	s_movk_i32 s87, 0x6000
	buffer_load_dwordx4 v138, s[16:19], 0 offen lds
	s_add_u32 s16, s20, 0x80000
	s_addc_u32 s7, s21, 0
	s_add_i32 s84, s76, 0x4000
	s_and_b32 s17, s7, 0xffff
	s_mov_b32 m0, s84
	s_add_i32 s85, s76, 0x6000
	buffer_load_dwordx4 v136, s[16:19], 0 offen lds
	s_mov_b32 m0, s85
	s_cmp_eq_u32 s4, 1
	buffer_load_dwordx4 v138, s[16:19], 0 offen lds
	s_cselect_b64 s[36:37], -1, 0
	s_cmp_lg_u32 s4, 1
	s_setprio 1
	s_cbranch_scc1 .LBB0_164
	s_setprio 0
	s_barrier

; #define PG8_STAGE(bufoff, gbase, voff) do { const __amdgpu_buffer_rsrc_t _rs = __builtin_amdgcn_make_buffer_rsrc((void*)(gbase), 0, 0x7fffffff, 0x00020000); _Pragma("unroll") for (int _i = 0; _i < 2; ++_i) \
;         __builtin_amdgcn_raw_ptr_buffer_load_lds(_rs, (LAS unsigned*)(lds + (bufoff) + ldsw + _i * 8192), 16, (int)(voff)[_i], 0, 0, 0); } while (0)
; #define PG8_BAR __builtin_amdgcn_s_barrier()
; template <class Epi, class Sched, bool F8 = false>
; __device__ __forceinline__ void gemm_phase(LAS unsigned char* lds, const int lda, const int ldb, const Sched& S, const Epi& E) {
;     ...
;     const int tid = tid_, wid = __builtin_amdgcn_readfirstlane(tid >> 6), lane = tid & 63, wr = wid >> 2, wc = wid & 3, fr = lane & 15, fq = lane >> 4;
;     unsigned voffA[2], voffB[2];
; #pragma unroll
;     for (int i = 0; i < 2; ++i) { int R, C; stage_rc(tid * 16 + i * 8192, R, C); const int Rb = Epi::PERM ? ((R & ~31) + perm32(R & 31)) : R;
;         voffA[i] = (unsigned)(R * lda + C * 2); voffB[i] = (unsigned)(Rb * 128 + C * 2); }
;     const size_t kstep = (size_t)(BK * 2), kstepB = 32768;
;     const size_t hstepA = (size_t)HALF * lda, hstepB = 16384; (void)ldb;
;     const unsigned ldsw = (unsigned)wid * 1024u;
;     const int aoff = lds_byte(wr * 64 + fr, fq * 8), boff = lds_byte(wc * 32 + fr, fq * 8);
;     ...
;     Unit cur, nxt; int ui = 0;
;     if (!S.next(0, cur)) return;
;     f32x4 acc[2][2][4][2];
; #pragma unroll
;     for (int a = 0; a < 2; ++a)
; #pragma unroll
;         for (int b = 0; b < 2; ++b)
; #pragma unroll
;             for (int m = 0; m < 4; ++m)
; #pragma unroll
;                 for (int n = 0; n < 2; ++n) acc[a][b][m][n] = (f32x4){0.f, 0.f, 0.f, 0.f};
;     bf16x8 At[4][2], B0[2][2], B1[2][2]; i32x8 At8[4], B08[2], B18[2];
;     const char* cA = cur.A; const char* cB = cur.B;
;     ...
;     PG8_STAGE(PG8_SB(0, 0), cB, voffB); PG8_STAGE(PG8_SB(0, 1), cB + hstepB, voffB); PG8_STAGE(PG8_SA(0, 0), cA, voffA); PG8_STAGE(PG8_SA(0, 1), cA + hstepA, voffA);
;     if (wr == 1) PG8_BAR;
.LBB0_395:
	v_bfe_i32 v3, v0, 27, 1
	v_lshlrev_b32_e32 v1, 4, v0
	v_lshrrev_b32_e32 v3, 22, v3
	v_add_u32_e32 v3, v1, v3
	v_and_b32_e32 v3, 0xfffffc00, v3
	v_sub_u32_e32 v3, v1, v3
	v_ashrrev_i32_e32 v2, 31, v0
	v_lshrrev_b32_e32 v4, 4, v3
	v_lshrrev_b32_e32 v2, 26, v2
	v_bitop3_b32 v3, v4, v3, 32 bitop3:0x6c
	v_add_u32_e32 v2, v0, v2
	v_ashrrev_i32_e32 v5, 31, v3
	v_ashrrev_i32_e32 v2, 6, v2
	v_lshrrev_b32_e32 v5, 26, v5
	v_lshlrev_b32_e32 v4, 3, v2
	v_add_u32_e32 v5, v3, v5
	v_and_b32_e32 v4, -16, v4
	v_ashrrev_i32_e32 v6, 6, v5
	v_and_b32_e32 v5, 0xc0, v5
	v_add_u32_e32 v4, v6, v4
	v_sub_u32_e32 v3, v3, v5
	v_mov_b32_e32 v5, 1
	v_lshlrev_b32_e32 v2, 5, v2
	v_ashrrev_i16_sdwa v3, v5, sext(v3) dst_sel:DWORD dst_unused:UNUSED_PAD src0_sel:DWORD src1_sel:BYTE_0
	v_lshlrev_b32_e32 v7, 1, v4
	v_lshrrev_b32_e32 v8, 2, v4
	v_and_b32_e32 v6, 3, v6
	s_mov_b32 s5, 0x1ffffe0
	v_and_b32_e32 v2, 32, v2
	v_bfe_i32 v3, v3, 0, 16
	v_and_b32_e32 v7, 24, v7
	v_and_b32_e32 v8, 4, v8
	v_and_or_b32 v6, v4, s5, v6
	v_or3_b32 v6, v6, v8, v7
	v_add_lshl_u32 v2, v2, v3, 1
	v_add_u32_e32 v1, 0x2000, v1
	v_lshl_add_u32 v176, v4, 12, v2
	v_lshl_add_u32 v177, v6, 7, v2
	v_ashrrev_i32_e32 v2, 31, v1
	v_lshrrev_b32_e32 v2, 22, v2
	v_add_u32_e32 v2, v1, v2
	v_ashrrev_i32_e32 v2, 10, v2
	v_mul_i32_i24_e32 v3, 0x400, v2
	v_sub_u32_e32 v1, v1, v3
	v_lshrrev_b32_e32 v3, 4, v1
	v_bitop3_b32 v1, v3, v1, 32 bitop3:0x6c
	v_ashrrev_i32_e32 v4, 31, v1
	s_ashr_i32 s37, s35, 6
	s_ashr_i32 s36, s35, 8
	v_lshrrev_b32_e32 v4, 26, v4
	s_waitcnt lgkmcnt(0)
	s_lshl_b32 s20, s37, 10
	v_lshlrev_b32_e32 v3, 3, v2
	v_add_u32_e32 v4, v1, v4
	s_add_u32 s0, s58, s0
	v_and_b32_e32 v3, -16, v3
	v_ashrrev_i32_e32 v6, 6, v4
	v_and_b32_e32 v4, 0xc0, v4
	s_addc_u32 s1, s59, s1
	v_add_u32_e32 v3, v6, v3
	v_sub_u32_e32 v1, v1, v4
	s_add_u32 s18, s0, s4
	v_lshlrev_b32_e32 v2, 5, v2
	v_ashrrev_i16_sdwa v1, v5, sext(v1) dst_sel:DWORD dst_unused:UNUSED_PAD src0_sel:DWORD src1_sel:BYTE_0
	v_lshlrev_b32_e32 v4, 1, v3
	v_lshrrev_b32_e32 v5, 2, v3
	v_and_b32_e32 v6, 3, v6
	s_addc_u32 s19, s1, 0
	s_add_i32 s74, s20, 0
	v_and_b32_e32 v2, 32, v2
	v_bfe_i32 v1, v1, 0, 16
	v_and_b32_e32 v4, 24, v4
	v_and_b32_e32 v5, 4, v5
	v_and_or_b32 v6, v3, s5, v6
	s_add_i32 s75, s74, 0x10000
	v_or3_b32 v4, v6, v5, v4
	v_add_lshl_u32 v1, v2, v1, 1
	s_and_b32 s5, s19, 0xffff
	s_mov_b32 s7, 0x20000
	s_brev_b32 s6, -2
	s_mov_b32 s4, s18
	s_mov_b32 m0, s75
	s_add_i32 s77, s74, 0x12000
	v_lshl_add_u32 v179, v4, 7, v1
	buffer_load_dwordx4 v177, s[4:7], 0 offen lds
	s_mov_b32 m0, s77
	v_lshl_add_u32 v178, v3, 12, v1
	buffer_load_dwordx4 v179, s[4:7], 0 offen lds
	s_add_u32 s4, s18, 0x4000
	s_addc_u32 s0, s19, 0
	s_add_i32 s78, s74, 0x14000
	s_and_b32 s5, s0, 0xffff
	s_mov_b32 m0, s78
	s_add_i32 s79, s74, 0x16000
	buffer_load_dwordx4 v177, s[4:7], 0 offen lds
	s_mov_b32 m0, s79
	s_add_i32 s80, s74, 0x2000
	buffer_load_dwordx4 v179, s[4:7], 0 offen lds
	s_and_b32 s5, s17, 0xffff
	s_mov_b32 s4, s16
	s_mov_b32 m0, s74
	s_mov_b32 s83, 0
	buffer_load_dwordx4 v176, s[4:7], 0 offen lds
	s_mov_b32 m0, s80
	s_nop 0
	buffer_load_dwordx4 v178, s[4:7], 0 offen lds
	s_add_u32 s4, s16, 0x80000
	s_addc_u32 s0, s17, 0
	s_add_i32 s81, s74, 0x4000
	s_and_b32 s5, s0, 0xffff
	s_mov_b32 m0, s81
	s_add_i32 s82, s74, 0x6000
	buffer_load_dwordx4 v176, s[4:7], 0 offen lds
	s_mov_b32 m0, s82
	s_cmp_eq_u32 s36, 1
	buffer_load_dwordx4 v178, s[4:7], 0 offen lds
	s_cselect_b64 s[20:21], -1, 0
	s_cmp_lg_u32 s36, 1
	s_setprio 1
	s_cbranch_scc1 .LBB0_397
	s_setprio 0
	s_barrier

; #define PG8_STAGE(bufoff, gbase, voff) do { const __amdgpu_buffer_rsrc_t _rs = __builtin_amdgcn_make_buffer_rsrc((void*)(gbase), 0, 0x7fffffff, 0x00020000); _Pragma("unroll") for (int _i = 0; _i < 2; ++_i) \
;         __builtin_amdgcn_raw_ptr_buffer_load_lds(_rs, (LAS unsigned*)(lds + (bufoff) + ldsw + _i * 8192), 16, (int)(voff)[_i], 0, 0, 0); } while (0)
; #define PG8_BAR __builtin_amdgcn_s_barrier()
; template <class Epi, class Sched, bool F8 = false>
; __device__ __forceinline__ void gemm_phase(LAS unsigned char* lds, const int lda, const int ldb, const Sched& S, const Epi& E) {
;     ...
;     const int tid = tid_, wid = __builtin_amdgcn_readfirstlane(tid >> 6), lane = tid & 63, wr = wid >> 2, wc = wid & 3, fr = lane & 15, fq = lane >> 4;
;     unsigned voffA[2], voffB[2];
; #pragma unroll
;     for (int i = 0; i < 2; ++i) { int R, C; stage_rc(tid * 16 + i * 8192, R, C); const int Rb = Epi::PERM ? ((R & ~31) + perm32(R & 31)) : R;
;         voffA[i] = (unsigned)(R * lda + C * 2); voffB[i] = (unsigned)(Rb * 128 + C * 2); }
;     const size_t kstep = (size_t)(BK * 2), kstepB = 32768;
;     const size_t hstepA = (size_t)HALF * lda, hstepB = 16384; (void)ldb;
;     const unsigned ldsw = (unsigned)wid * 1024u;
;     const int aoff = lds_byte(wr * 64 + fr, fq * 8), boff = lds_byte(wc * 32 + fr, fq * 8);
;     ...
;     Unit cur, nxt; int ui = 0;
;     if (!S.next(0, cur)) return;
;     f32x4 acc[2][2][4][2];
; #pragma unroll
;     for (int a = 0; a < 2; ++a)
; #pragma unroll
;         for (int b = 0; b < 2; ++b)
; #pragma unroll
;             for (int m = 0; m < 4; ++m)
; #pragma unroll
;                 for (int n = 0; n < 2; ++n) acc[a][b][m][n] = (f32x4){0.f, 0.f, 0.f, 0.f};
;     bf16x8 At[4][2], B0[2][2], B1[2][2]; i32x8 At8[4], B08[2], B18[2];
;     const char* cA = cur.A; const char* cB = cur.B;
;     ...
;     PG8_STAGE(PG8_SB(0, 0), cB, voffB); PG8_STAGE(PG8_SB(0, 1), cB + hstepB, voffB); PG8_STAGE(PG8_SA(0, 0), cA, voffA); PG8_STAGE(PG8_SA(0, 1), cA + hstepA, voffA);
;     if (wr == 1) PG8_BAR;
.LBB0_477:
	v_bfe_i32 v3, v0, 27, 1
	v_lshlrev_b32_e32 v1, 4, v0
	v_lshrrev_b32_e32 v3, 22, v3
	v_add_u32_e32 v3, v1, v3
	v_and_b32_e32 v3, 0xfffffc00, v3
	v_sub_u32_e32 v3, v1, v3
	v_ashrrev_i32_e32 v2, 31, v0
	v_lshrrev_b32_e32 v4, 4, v3
	v_lshrrev_b32_e32 v2, 26, v2
	v_bitop3_b32 v3, v4, v3, 32 bitop3:0x6c
	v_add_u32_e32 v2, v0, v2
	v_ashrrev_i32_e32 v5, 31, v3
	v_ashrrev_i32_e32 v2, 6, v2
	v_lshrrev_b32_e32 v5, 26, v5
	v_lshlrev_b32_e32 v4, 3, v2
	v_add_u32_e32 v5, v3, v5
	v_and_b32_e32 v4, -16, v4
	v_ashrrev_i32_e32 v6, 6, v5
	v_and_b32_e32 v5, 0xc0, v5
	v_add_u32_e32 v4, v6, v4
	v_sub_u32_e32 v3, v3, v5
	v_mov_b32_e32 v5, 1
	v_lshlrev_b32_e32 v2, 5, v2
	v_ashrrev_i16_sdwa v3, v5, sext(v3) dst_sel:DWORD dst_unused:UNUSED_PAD src0_sel:DWORD src1_sel:BYTE_0
	v_lshlrev_b32_e32 v7, 1, v4
	v_lshrrev_b32_e32 v8, 2, v4
	v_and_b32_e32 v6, 3, v6
	s_mov_b32 s1, 0x1ffffe0
	v_and_b32_e32 v2, 32, v2
	v_bfe_i32 v3, v3, 0, 16
	v_and_b32_e32 v7, 24, v7
	v_and_b32_e32 v8, 4, v8
	v_and_or_b32 v6, v4, s1, v6
	v_or3_b32 v6, v6, v8, v7
	v_add_lshl_u32 v2, v2, v3, 1
	v_add_u32_e32 v1, 0x2000, v1
	v_lshl_add_u32 v148, v4, 12, v2
	v_lshl_add_u32 v149, v6, 7, v2
	v_ashrrev_i32_e32 v2, 31, v1
	v_lshrrev_b32_e32 v2, 22, v2
	v_add_u32_e32 v2, v1, v2
	v_ashrrev_i32_e32 v2, 10, v2
	v_mul_i32_i24_e32 v3, 0x400, v2
	v_sub_u32_e32 v1, v1, v3
	v_lshrrev_b32_e32 v3, 4, v1
	v_bitop3_b32 v1, v3, v1, 32 bitop3:0x6c
	v_ashrrev_i32_e32 v4, 31, v1
	v_lshrrev_b32_e32 v4, 26, v4
	v_lshlrev_b32_e32 v3, 3, v2
	v_add_u32_e32 v4, v1, v4
	v_and_b32_e32 v3, -16, v3
	v_ashrrev_i32_e32 v6, 6, v4
	v_add_u32_e32 v3, v6, v3
	v_and_b32_e32 v6, 3, v6
	v_and_b32_e32 v4, 0xc0, v4
	v_and_or_b32 v6, v3, s1, v6
	s_ashr_i32 s1, s9, 6
	v_sub_u32_e32 v1, v1, v4
	s_lshl_b32 s8, s1, 10
	v_lshlrev_b32_e32 v2, 5, v2
	v_ashrrev_i16_sdwa v1, v5, sext(v1) dst_sel:DWORD dst_unused:UNUSED_PAD src0_sel:DWORD src1_sel:BYTE_0
	v_lshlrev_b32_e32 v4, 1, v3
	v_lshrrev_b32_e32 v5, 2, v3
	s_add_i32 s67, s8, 0
	v_and_b32_e32 v2, 32, v2
	v_bfe_i32 v1, v1, 0, 16
	v_and_b32_e32 v4, 24, v4
	v_and_b32_e32 v5, 4, v5
	s_add_i32 s70, s67, 0x10000
	v_or3_b32 v4, v6, v5, v4
	v_add_lshl_u32 v1, v2, v1, 1
	s_waitcnt lgkmcnt(0)
	s_and_b32 s5, s19, 0xffff
	s_mov_b32 s7, 0x20000
	s_brev_b32 s6, -2
	s_mov_b32 s4, s18
	s_mov_b32 m0, s70
	s_add_i32 s71, s67, 0x12000
	s_ashr_i32 s0, s9, 8
	v_lshl_add_u32 v151, v4, 7, v1
	buffer_load_dwordx4 v149, s[4:7], 0 offen lds
	s_mov_b32 m0, s71
	v_lshl_add_u32 v150, v3, 12, v1
	buffer_load_dwordx4 v151, s[4:7], 0 offen lds
	s_add_u32 s4, s18, 0x4000
	s_addc_u32 s5, s19, 0
	s_add_i32 s72, s67, 0x14000
	s_and_b32 s5, s5, 0xffff
	s_mov_b32 m0, s72
	s_add_i32 s73, s67, 0x16000
	buffer_load_dwordx4 v149, s[4:7], 0 offen lds
	s_mov_b32 m0, s73
	s_add_i32 s74, s67, 0x2000
	buffer_load_dwordx4 v151, s[4:7], 0 offen lds
	s_and_b32 s5, s17, 0xffff
	s_mov_b32 s4, s16
	s_mov_b32 m0, s67
	s_mov_b32 s8, 0
	buffer_load_dwordx4 v148, s[4:7], 0 offen lds
	s_mov_b32 m0, s74
	s_movk_i32 s77, 0x4000
	buffer_load_dwordx4 v150, s[4:7], 0 offen lds
	s_add_u32 s4, s16, 0x80000
	s_addc_u32 s5, s17, 0
	s_add_i32 s75, s67, 0x4000
	s_and_b32 s5, s5, 0xffff
	s_mov_b32 m0, s75
	s_add_i32 s76, s67, 0x6000
	buffer_load_dwordx4 v148, s[4:7], 0 offen lds
	s_mov_b32 m0, s76
	s_cmp_eq_u32 s0, 1
	buffer_load_dwordx4 v150, s[4:7], 0 offen lds
	s_cselect_b64 s[14:15], -1, 0
	s_cmp_lg_u32 s0, 1
	s_movk_i32 s78, 0x6000
	s_setprio 1
	s_cbranch_scc1 .LBB0_479
	s_setprio 0
	s_barrier

; #define PG8_STAGE(bufoff, gbase, voff) do { const __amdgpu_buffer_rsrc_t _rs = __builtin_amdgcn_make_buffer_rsrc((void*)(gbase), 0, 0x7fffffff, 0x00020000); _Pragma("unroll") for (int _i = 0; _i < 2; ++_i) \
;         __builtin_amdgcn_raw_ptr_buffer_load_lds(_rs, (LAS unsigned*)(lds + (bufoff) + ldsw + _i * 8192), 16, (int)(voff)[_i], 0, 0, 0); } while (0)
; #define PG8_BAR __builtin_amdgcn_s_barrier()
; template <class Epi, class Sched, bool F8 = false>
; __device__ __forceinline__ void gemm_phase(LAS unsigned char* lds, const int lda, const int ldb, const Sched& S, const Epi& E) {
;     ...
;     const int tid = tid_, wid = __builtin_amdgcn_readfirstlane(tid >> 6), lane = tid & 63, wr = wid >> 2, wc = wid & 3, fr = lane & 15, fq = lane >> 4;
;     unsigned voffA[2], voffB[2];
; #pragma unroll
;     for (int i = 0; i < 2; ++i) { int R, C; stage_rc(tid * 16 + i * 8192, R, C); const int Rb = Epi::PERM ? ((R & ~31) + perm32(R & 31)) : R;
;         voffA[i] = (unsigned)(R * lda + C * 2); voffB[i] = (unsigned)(Rb * 128 + C * 2); }
;     const size_t kstep = (size_t)(BK * 2), kstepB = 32768;
;     const size_t hstepA = (size_t)HALF * lda, hstepB = 16384; (void)ldb;
;     const unsigned ldsw = (unsigned)wid * 1024u;
;     const int aoff = lds_byte(wr * 64 + fr, fq * 8), boff = lds_byte(wc * 32 + fr, fq * 8);
;     ...
;     Unit cur, nxt; int ui = 0;
;     if (!S.next(0, cur)) return;
;     f32x4 acc[2][2][4][2];
; #pragma unroll
;     for (int a = 0; a < 2; ++a)
; #pragma unroll
;         for (int b = 0; b < 2; ++b)
; #pragma unroll
;             for (int m = 0; m < 4; ++m)
; #pragma unroll
;                 for (int n = 0; n < 2; ++n) acc[a][b][m][n] = (f32x4){0.f, 0.f, 0.f, 0.f};
;     bf16x8 At[4][2], B0[2][2], B1[2][2]; i32x8 At8[4], B08[2], B18[2];
;     const char* cA = cur.A; const char* cB = cur.B;
;     ...
;     PG8_STAGE(PG8_SB(0, 0), cB, voffB); PG8_STAGE(PG8_SB(0, 1), cB + hstepB, voffB); PG8_STAGE(PG8_SA(0, 0), cA, voffA); PG8_STAGE(PG8_SA(0, 1), cA + hstepA, voffA);
;     if (wr == 1) PG8_BAR;
.LBB0_620:
	v_bfe_i32 v3, v0, 27, 1
	v_lshlrev_b32_e32 v1, 4, v0
	v_lshrrev_b32_e32 v3, 22, v3
	v_add_u32_e32 v3, v1, v3
	v_and_b32_e32 v3, 0xfffffc00, v3
	v_sub_u32_e32 v3, v1, v3
	v_ashrrev_i32_e32 v2, 31, v0
	v_lshrrev_b32_e32 v4, 4, v3
	v_lshrrev_b32_e32 v2, 26, v2
	v_bitop3_b32 v3, v4, v3, 32 bitop3:0x6c
	v_add_u32_e32 v2, v0, v2
	v_ashrrev_i32_e32 v5, 31, v3
	v_ashrrev_i32_e32 v2, 6, v2
	v_lshrrev_b32_e32 v5, 26, v5
	v_lshlrev_b32_e32 v4, 3, v2
	v_add_u32_e32 v5, v3, v5
	v_and_b32_e32 v4, -16, v4
	v_ashrrev_i32_e32 v6, 6, v5
	v_and_b32_e32 v5, 0xc0, v5
	v_add_u32_e32 v4, v6, v4
	v_sub_u32_e32 v3, v3, v5
	v_mov_b32_e32 v5, 1
	v_lshlrev_b32_e32 v2, 5, v2
	v_ashrrev_i16_sdwa v3, v5, sext(v3) dst_sel:DWORD dst_unused:UNUSED_PAD src0_sel:DWORD src1_sel:BYTE_0
	v_lshlrev_b32_e32 v7, 1, v4
	v_lshrrev_b32_e32 v8, 2, v4
	v_and_b32_e32 v6, 3, v6
	s_mov_b32 s1, 0x1ffffe0
	v_and_b32_e32 v2, 32, v2
	v_bfe_i32 v3, v3, 0, 16
	v_and_b32_e32 v7, 24, v7
	v_and_b32_e32 v8, 4, v8
	v_and_or_b32 v6, v4, s1, v6
	v_or3_b32 v6, v6, v8, v7
	v_add_lshl_u32 v2, v2, v3, 1
	v_add_u32_e32 v1, 0x2000, v1
	v_lshl_add_u32 v138, v4, 13, v2
	v_lshl_add_u32 v139, v6, 7, v2
	v_ashrrev_i32_e32 v2, 31, v1
	v_lshrrev_b32_e32 v2, 22, v2
	v_add_u32_e32 v2, v1, v2
	v_ashrrev_i32_e32 v2, 10, v2
	v_mul_i32_i24_e32 v3, 0x400, v2
	v_sub_u32_e32 v1, v1, v3
	v_lshrrev_b32_e32 v3, 4, v1
	v_bitop3_b32 v1, v3, v1, 32 bitop3:0x6c
	v_ashrrev_i32_e32 v4, 31, v1
	v_lshrrev_b32_e32 v4, 26, v4
	v_lshlrev_b32_e32 v3, 3, v2
	v_add_u32_e32 v4, v1, v4
	s_ashr_i32 s0, s26, 6
	v_and_b32_e32 v3, -16, v3
	v_ashrrev_i32_e32 v6, 6, v4
	v_and_b32_e32 v4, 0xc0, v4
	v_add_u32_e32 v3, v6, v3
	v_sub_u32_e32 v1, v1, v4
	s_lshl_b32 s14, s0, 10
	v_lshlrev_b32_e32 v2, 5, v2
	v_ashrrev_i16_sdwa v1, v5, sext(v1) dst_sel:DWORD dst_unused:UNUSED_PAD src0_sel:DWORD src1_sel:BYTE_0
	v_lshlrev_b32_e32 v4, 1, v3
	v_lshrrev_b32_e32 v5, 2, v3
	v_and_b32_e32 v6, 3, v6
	s_add_i32 s61, s14, 0
	v_and_b32_e32 v2, 32, v2
	v_bfe_i32 v1, v1, 0, 16
	v_and_b32_e32 v4, 24, v4
	v_and_b32_e32 v5, 4, v5
	v_and_or_b32 v6, v3, s1, v6
	s_add_i32 s73, s61, 0x10000
	v_or3_b32 v4, v6, v5, v4
	v_add_lshl_u32 v1, v2, v1, 1
	s_and_b32 s5, s19, 0xffff
	s_mov_b32 s7, 0x20000
	s_brev_b32 s6, -2
	s_mov_b32 s4, s18
	s_mov_b32 m0, s73
	s_add_i32 s74, s61, 0x12000
	v_lshl_add_u32 v141, v4, 7, v1
	s_ashr_i32 s1, s26, 8
	buffer_load_dwordx4 v139, s[4:7], 0 offen lds
	s_mov_b32 m0, s74
	v_lshl_add_u32 v140, v3, 13, v1
	buffer_load_dwordx4 v141, s[4:7], 0 offen lds
	s_add_u32 s4, s18, 0x4000
	s_addc_u32 s5, s19, 0
	s_add_i32 s75, s61, 0x14000
	s_and_b32 s5, s5, 0xffff
	s_mov_b32 m0, s75
	s_add_i32 s76, s61, 0x16000
	buffer_load_dwordx4 v139, s[4:7], 0 offen lds
	s_mov_b32 m0, s76
	s_add_i32 s77, s61, 0x2000
	buffer_load_dwordx4 v141, s[4:7], 0 offen lds
	s_and_b32 s5, s17, 0xffff
	s_mov_b32 s4, s16
	s_mov_b32 m0, s61
	s_mov_b32 s80, 0
	buffer_load_dwordx4 v138, s[4:7], 0 offen lds
	s_mov_b32 m0, s77
	s_nop 0
	buffer_load_dwordx4 v140, s[4:7], 0 offen lds
	s_add_u32 s4, s16, 0x100000
	s_addc_u32 s5, s17, 0
	s_add_i32 s78, s61, 0x4000
	s_and_b32 s5, s5, 0xffff
	s_mov_b32 m0, s78
	s_add_i32 s79, s61, 0x6000
	buffer_load_dwordx4 v138, s[4:7], 0 offen lds
	s_mov_b32 m0, s79
	s_cmp_eq_u32 s1, 1
	buffer_load_dwordx4 v140, s[4:7], 0 offen lds
	s_cselect_b64 s[14:15], -1, 0
	s_cmp_lg_u32 s1, 1
	s_setprio 1
	s_cbranch_scc1 .LBB0_622
	s_setprio 0
	s_barrier

; #define PG8_STAGE(bufoff, gbase, voff) do { const __amdgpu_buffer_rsrc_t _rs = __builtin_amdgcn_make_buffer_rsrc((void*)(gbase), 0, 0x7fffffff, 0x00020000); _Pragma("unroll") for (int _i = 0; _i < 2; ++_i) \
;         __builtin_amdgcn_raw_ptr_buffer_load_lds(_rs, (LAS unsigned*)(lds + (bufoff) + ldsw + _i * 8192), 16, (int)(voff)[_i], 0, 0, 0); } while (0)
; #define PG8_BAR __builtin_amdgcn_s_barrier()
; template <class Epi, class Sched, bool F8 = false>
; __device__ __forceinline__ void gemm_phase(LAS unsigned char* lds, const int lda, const int ldb, const Sched& S, const Epi& E) {
;     ...
;     const int tid = tid_, wid = __builtin_amdgcn_readfirstlane(tid >> 6), lane = tid & 63, wr = wid >> 2, wc = wid & 3, fr = lane & 15, fq = lane >> 4;
;     unsigned voffA[2], voffB[2];
; #pragma unroll
;     for (int i = 0; i < 2; ++i) { int R, C; stage_rc(tid * 16 + i * 8192, R, C); const int Rb = Epi::PERM ? ((R & ~31) + perm32(R & 31)) : R;
;         voffA[i] = (unsigned)(R * lda + C * 2); voffB[i] = (unsigned)(Rb * 128 + C * 2); }
;     const size_t kstep = (size_t)(BK * 2), kstepB = 32768;
;     const size_t hstepA = (size_t)HALF * lda, hstepB = 16384; (void)ldb;
;     const unsigned ldsw = (unsigned)wid * 1024u;
;     const int aoff = lds_byte(wr * 64 + fr, fq * 8), boff = lds_byte(wc * 32 + fr, fq * 8);
;     ...
;     Unit cur, nxt; int ui = 0;
;     if (!S.next(0, cur)) return;
;     f32x4 acc[2][2][4][2];
; #pragma unroll
;     for (int a = 0; a < 2; ++a)
; #pragma unroll
;         for (int b = 0; b < 2; ++b)
; #pragma unroll
;             for (int m = 0; m < 4; ++m)
; #pragma unroll
;                 for (int n = 0; n < 2; ++n) acc[a][b][m][n] = (f32x4){0.f, 0.f, 0.f, 0.f};
;     bf16x8 At[4][2], B0[2][2], B1[2][2]; i32x8 At8[4], B08[2], B18[2];
;     const char* cA = cur.A; const char* cB = cur.B;
;     ...
;     PG8_STAGE(PG8_SB(0, 0), cB, voffB); PG8_STAGE(PG8_SB(0, 1), cB + hstepB, voffB); PG8_STAGE(PG8_SA(0, 0), cA, voffA); PG8_STAGE(PG8_SA(0, 1), cA + hstepA, voffA);
;     if (wr == 1) PG8_BAR;
.LBB0_770:
	v_bfe_i32 v3, v0, 27, 1
	v_lshlrev_b32_e32 v1, 4, v0
	v_lshrrev_b32_e32 v3, 22, v3
	v_add_u32_e32 v3, v1, v3
	v_and_b32_e32 v3, 0xfffffc00, v3
	v_sub_u32_e32 v3, v1, v3
	v_ashrrev_i32_e32 v2, 31, v0
	v_lshrrev_b32_e32 v4, 4, v3
	v_lshrrev_b32_e32 v2, 26, v2
	v_bitop3_b32 v3, v4, v3, 32 bitop3:0x6c
	v_add_u32_e32 v2, v0, v2
	v_ashrrev_i32_e32 v5, 31, v3
	v_ashrrev_i32_e32 v2, 6, v2
	v_lshrrev_b32_e32 v5, 26, v5
	v_lshlrev_b32_e32 v4, 3, v2
	v_add_u32_e32 v5, v3, v5
	v_and_b32_e32 v4, -16, v4
	v_ashrrev_i32_e32 v6, 6, v5
	v_and_b32_e32 v5, 0xc0, v5
	v_add_u32_e32 v4, v6, v4
	v_sub_u32_e32 v3, v3, v5
	v_mov_b32_e32 v5, 1
	v_lshlrev_b32_e32 v2, 5, v2
	v_ashrrev_i16_sdwa v3, v5, sext(v3) dst_sel:DWORD dst_unused:UNUSED_PAD src0_sel:DWORD src1_sel:BYTE_0
	v_lshlrev_b32_e32 v7, 1, v4
	v_lshrrev_b32_e32 v8, 2, v4
	v_and_b32_e32 v6, 3, v6
	s_mov_b32 s1, 0x1ffffe0
	v_and_b32_e32 v2, 32, v2
	v_bfe_i32 v3, v3, 0, 16
	v_and_b32_e32 v7, 24, v7
	v_and_b32_e32 v8, 4, v8
	v_and_or_b32 v6, v4, s1, v6
	v_or3_b32 v6, v6, v8, v7
	v_add_lshl_u32 v2, v2, v3, 1
	v_add_u32_e32 v1, 0x2000, v1
	v_lshl_add_u32 v175, v4, 13, v2
	v_lshl_add_u32 v177, v6, 7, v2
	v_ashrrev_i32_e32 v2, 31, v1
	v_lshrrev_b32_e32 v2, 22, v2
	v_add_u32_e32 v2, v1, v2
	v_ashrrev_i32_e32 v2, 10, v2
	v_mul_i32_i24_e32 v3, 0x400, v2
	v_sub_u32_e32 v1, v1, v3
	v_lshrrev_b32_e32 v3, 4, v1
	v_bitop3_b32 v1, v3, v1, 32 bitop3:0x6c
	v_ashrrev_i32_e32 v4, 31, v1
	v_lshrrev_b32_e32 v4, 26, v4
	v_lshlrev_b32_e32 v3, 3, v2
	v_add_u32_e32 v4, v1, v4
	s_ashr_i32 s0, s8, 6
	v_and_b32_e32 v3, -16, v3
	v_ashrrev_i32_e32 v6, 6, v4
	v_and_b32_e32 v4, 0xc0, v4
	v_add_u32_e32 v3, v6, v3
	v_sub_u32_e32 v1, v1, v4
	s_lshl_b32 s9, s0, 10
	v_lshlrev_b32_e32 v2, 5, v2
	v_ashrrev_i16_sdwa v1, v5, sext(v1) dst_sel:DWORD dst_unused:UNUSED_PAD src0_sel:DWORD src1_sel:BYTE_0
	v_lshlrev_b32_e32 v4, 1, v3
	v_lshrrev_b32_e32 v5, 2, v3
	v_and_b32_e32 v6, 3, v6
	s_add_i32 s51, s9, 0
	v_and_b32_e32 v2, 32, v2
	v_bfe_i32 v1, v1, 0, 16
	v_and_b32_e32 v4, 24, v4
	v_and_b32_e32 v5, 4, v5
	v_and_or_b32 v6, v3, s1, v6
	s_add_i32 s68, s51, 0x10000
	v_or3_b32 v4, v6, v5, v4
	v_add_lshl_u32 v1, v2, v1, 1
	s_and_b32 s13, s7, 0xffff
	s_mov_b32 s15, 0x20000
	s_brev_b32 s14, -2
	s_mov_b32 s12, s6
	s_mov_b32 m0, s68
	s_add_i32 s69, s51, 0x12000
	v_lshl_add_u32 v193, v4, 7, v1
	s_ashr_i32 s1, s8, 8
	buffer_load_dwordx4 v177, s[12:15], 0 offen lds
	s_mov_b32 m0, s69
	v_lshl_add_u32 v179, v3, 13, v1
	buffer_load_dwordx4 v193, s[12:15], 0 offen lds
	s_add_u32 s12, s6, 0x4000
	s_addc_u32 s9, s7, 0
	s_add_i32 s70, s51, 0x14000
	s_and_b32 s13, s9, 0xffff
	s_mov_b32 m0, s70
	s_add_i32 s71, s51, 0x16000
	buffer_load_dwordx4 v177, s[12:15], 0 offen lds
	s_mov_b32 m0, s71
	s_add_i32 s72, s51, 0x2000
	buffer_load_dwordx4 v193, s[12:15], 0 offen lds
	s_and_b32 s13, s5, 0xffff
	s_mov_b32 s12, s4
	s_mov_b32 m0, s51
	s_mov_b32 s75, 0
	buffer_load_dwordx4 v175, s[12:15], 0 offen lds
	s_mov_b32 m0, s72
	s_nop 0
	buffer_load_dwordx4 v179, s[12:15], 0 offen lds
	s_add_u32 s12, s4, 0x100000
	s_addc_u32 s9, s5, 0
	s_add_i32 s73, s51, 0x4000
	s_and_b32 s13, s9, 0xffff
	s_mov_b32 m0, s73
	s_add_i32 s74, s51, 0x6000
	buffer_load_dwordx4 v175, s[12:15], 0 offen lds
	s_mov_b32 m0, s74
	s_cmp_eq_u32 s1, 1
	buffer_load_dwordx4 v179, s[12:15], 0 offen lds
	s_mov_b32 s9, 4
	s_cselect_b64 s[26:27], -1, 0
	s_cmp_lg_u32 s1, 1
	s_setprio 1
	s_cbranch_scc1 .LBB0_772
	s_mov_b32 s9, 8
	s_setprio 0
	s_barrier

; #define PG8_STAGE(bufoff, gbase, voff) do { const __amdgpu_buffer_rsrc_t _rs = __builtin_amdgcn_make_buffer_rsrc((void*)(gbase), 0, 0x7fffffff, 0x00020000); _Pragma("unroll") for (int _i = 0; _i < 2; ++_i) \
;         __builtin_amdgcn_raw_ptr_buffer_load_lds(_rs, (LAS unsigned*)(lds + (bufoff) + ldsw + _i * 8192), 16, (int)(voff)[_i], 0, 0, 0); } while (0)
; #define PG8_BAR __builtin_amdgcn_s_barrier()
; template <class Epi, class Sched, bool F8 = false>
; __device__ __forceinline__ void gemm_phase(LAS unsigned char* lds, const int lda, const int ldb, const Sched& S, const Epi& E) {
;     ...
;     const int tid = tid_, wid = __builtin_amdgcn_readfirstlane(tid >> 6), lane = tid & 63, wr = wid >> 2, wc = wid & 3, fr = lane & 15, fq = lane >> 4;
;     unsigned voffA[2], voffB[2];
; #pragma unroll
;     for (int i = 0; i < 2; ++i) { int R, C; stage_rc(tid * 16 + i * 8192, R, C); const int Rb = Epi::PERM ? ((R & ~31) + perm32(R & 31)) : R;
;         voffA[i] = (unsigned)(R * lda + C * 2); voffB[i] = (unsigned)(Rb * 128 + C * 2); }
;     const size_t kstep = (size_t)(BK * 2), kstepB = 32768;
;     const size_t hstepA = (size_t)HALF * lda, hstepB = 16384; (void)ldb;
;     const unsigned ldsw = (unsigned)wid * 1024u;
;     const int aoff = lds_byte(wr * 64 + fr, fq * 8), boff = lds_byte(wc * 32 + fr, fq * 8);
;     ...
;     Unit cur, nxt; int ui = 0;
;     if (!S.next(0, cur)) return;
;     f32x4 acc[2][2][4][2];
; #pragma unroll
;     for (int a = 0; a < 2; ++a)
; #pragma unroll
;         for (int b = 0; b < 2; ++b)
; #pragma unroll
;             for (int m = 0; m < 4; ++m)
; #pragma unroll
;                 for (int n = 0; n < 2; ++n) acc[a][b][m][n] = (f32x4){0.f, 0.f, 0.f, 0.f};
;     bf16x8 At[4][2], B0[2][2], B1[2][2]; i32x8 At8[4], B08[2], B18[2];
;     const char* cA = cur.A; const char* cB = cur.B;
;     ...
;     PG8_STAGE(PG8_SB(0, 0), cB, voffB); PG8_STAGE(PG8_SB(0, 1), cB + hstepB, voffB); PG8_STAGE(PG8_SA(0, 0), cA, voffA); PG8_STAGE(PG8_SA(0, 1), cA + hstepA, voffA);
;     if (wr == 1) PG8_BAR;
.LBB0_923:
	v_bfe_i32 v3, v0, 27, 1
	v_lshlrev_b32_e32 v1, 4, v0
	v_lshrrev_b32_e32 v3, 22, v3
	v_add_u32_e32 v3, v1, v3
	v_and_b32_e32 v3, 0xfffffc00, v3
	v_sub_u32_e32 v3, v1, v3
	v_lshrrev_b32_e32 v4, 4, v3
	v_ashrrev_i32_e32 v2, 31, v0
	v_bitop3_b32 v3, v4, v3, 32 bitop3:0x6c
	v_lshrrev_b32_e32 v2, 26, v2
	v_ashrrev_i32_e32 v5, 31, v3
	v_add_u32_e32 v2, v0, v2
	v_lshrrev_b32_e32 v5, 26, v5
	v_ashrrev_i32_e32 v2, 6, v2
	v_add_u32_e32 v5, v3, v5
	v_lshlrev_b32_e32 v4, 3, v2
	v_ashrrev_i32_e32 v6, 6, v5
	v_and_b32_e32 v5, 0xc0, v5
	v_and_b32_e32 v4, -16, v4
	v_sub_u32_e32 v3, v3, v5
	v_mov_b32_e32 v5, 1
	v_add_u32_e32 v4, v6, v4
	v_lshlrev_b32_e32 v2, 5, v2
	v_ashrrev_i16_sdwa v3, v5, sext(v3) dst_sel:DWORD dst_unused:UNUSED_PAD src0_sel:DWORD src1_sel:BYTE_0
	v_and_b32_e32 v2, 32, v2
	v_bfe_i32 v3, v3, 0, 16
	v_lshlrev_b32_e32 v7, 1, v4
	v_lshrrev_b32_e32 v8, 2, v4
	v_and_b32_e32 v6, 3, v6
	s_mov_b32 s1, 0x1ffffe0
	v_and_b32_e32 v7, 24, v7
	v_and_b32_e32 v8, 4, v8
	v_and_or_b32 v6, v4, s1, v6
	v_add_lshl_u32 v2, v2, v3, 1
	s_movk_i32 s6, 0x5600
	v_or3_b32 v6, v6, v8, v7
	v_mad_u64_u32 v[128:129], s[4:5], v4, s6, v[2:3]
	v_add_u32_e32 v1, 0x2000, v1
	v_lshl_add_u32 v129, v6, 7, v2
	v_ashrrev_i32_e32 v2, 31, v1
	v_lshrrev_b32_e32 v2, 22, v2
	v_add_u32_e32 v2, v1, v2
	v_ashrrev_i32_e32 v2, 10, v2
	v_mul_i32_i24_e32 v3, 0x400, v2
	v_sub_u32_e32 v1, v1, v3
	v_lshrrev_b32_e32 v3, 4, v1
	v_bitop3_b32 v1, v3, v1, 32 bitop3:0x6c
	v_ashrrev_i32_e32 v4, 31, v1
	v_lshrrev_b32_e32 v4, 26, v4
	v_add_u32_e32 v4, v1, v4
	v_ashrrev_i32_e32 v6, 6, v4
	v_and_b32_e32 v4, 0xc0, v4
	v_lshlrev_b32_e32 v3, 3, v2
	v_sub_u32_e32 v1, v1, v4
	s_ashr_i32 s0, s16, 6
	v_and_b32_e32 v3, -16, v3
	v_lshlrev_b32_e32 v2, 5, v2
	v_ashrrev_i16_sdwa v1, v5, sext(v1) dst_sel:DWORD dst_unused:UNUSED_PAD src0_sel:DWORD src1_sel:BYTE_0
	v_add_u32_e32 v3, v6, v3
	v_and_b32_e32 v2, 32, v2
	v_bfe_i32 v1, v1, 0, 16
	s_lshl_b32 s17, s0, 10
	v_lshlrev_b32_e32 v4, 1, v3
	v_lshrrev_b32_e32 v5, 2, v3
	v_and_b32_e32 v6, 3, v6
	v_add_lshl_u32 v2, v2, v1, 1
	s_add_i32 s48, s17, 0
	v_and_b32_e32 v4, 24, v4
	v_and_b32_e32 v5, 4, v5
	v_and_or_b32 v6, v3, s1, v6
	v_mad_u64_u32 v[130:131], s[4:5], v3, s6, v[2:3]
	s_add_i32 s49, s48, 0x10000
	v_or3_b32 v4, v6, v5, v4
	s_and_b32 s5, s15, 0xffff
	s_mov_b32 s7, 0x20000
	s_brev_b32 s6, -2
	s_mov_b32 s4, s14
	s_mov_b32 m0, s49
	s_add_i32 s50, s48, 0x12000
	v_lshl_add_u32 v131, v4, 7, v2
	s_ashr_i32 s1, s16, 8
	buffer_load_dwordx4 v129, s[4:7], 0 offen lds
	s_mov_b32 m0, s50
	s_mov_b32 s67, 0
	buffer_load_dwordx4 v131, s[4:7], 0 offen lds
	s_add_u32 s4, s14, 0x4000
	s_addc_u32 s5, s15, 0
	s_add_i32 s51, s48, 0x14000
	s_and_b32 s5, s5, 0xffff
	s_mov_b32 m0, s51
	s_add_i32 s52, s48, 0x16000
	buffer_load_dwordx4 v129, s[4:7], 0 offen lds
	s_mov_b32 m0, s52
	s_add_i32 s53, s48, 0x2000
	buffer_load_dwordx4 v131, s[4:7], 0 offen lds
	s_and_b32 s5, s13, 0xffff
	s_mov_b32 s4, s12
	s_mov_b32 m0, s48
	s_nop 0
	buffer_load_dwordx4 v128, s[4:7], 0 offen lds
	s_mov_b32 m0, s53
	s_nop 0
	buffer_load_dwordx4 v130, s[4:7], 0 offen lds
	s_add_u32 s4, s12, 0x2b0000
	s_addc_u32 s5, s13, 0
	s_add_i32 s61, s48, 0x4000
	s_and_b32 s5, s5, 0xffff
	s_mov_b32 m0, s61
	s_add_i32 s66, s48, 0x6000
	buffer_load_dwordx4 v128, s[4:7], 0 offen lds
	s_mov_b32 m0, s66
	s_cmp_eq_u32 s1, 1
	buffer_load_dwordx4 v130, s[4:7], 0 offen lds
	s_cselect_b64 s[26:27], -1, 0
	s_cmp_lg_u32 s1, 1
	s_setprio 1
	s_cbranch_scc1 .LBB0_925
	s_setprio 0
	s_barrier
